# cache policy: nt on residual-epilogue h loads only (stores default), on top of v28 (measurement 1)
# speedup vs baseline: 1.0011x; 1.0011x over previous
.LBB0_394:
	s_add_i32 s2, s47, 0xffffff80
	s_ashr_i32 s20, s47, 31
	s_cmpk_lt_i32 s47, 0x80
	v_readlane_b32 s52, v239, 17
	s_cselect_b32 s21, s20, 0
	s_cselect_b32 s20, s47, s2
	v_readlane_b32 s53, v239, 18
	v_readlane_b32 s56, v239, 21
	v_readlane_b32 s57, v239, 22
	s_movk_i32 s23, 0x2400
	s_cselect_b32 s2, s87, s9
	s_cselect_b32 s22, s86, s8
	s_cselect_b32 s24, s53, s57
	s_cselect_b32 s25, s52, s56
	s_cselect_b32 s26, s23, 0x4800
	s_lshl_b64 s[20:21], s[20:21], 20
	s_add_u32 s22, s22, s20
	s_addc_u32 s23, s2, s21
	s_add_u32 s20, s25, s20
	s_addc_u32 s21, s24, s21
	s_cmp_gt_i32 s47, 63
	s_cselect_b32 s2, s26, 0
	v_lshl_or_b32 v158, s48, 8, v167
	s_lshl_b32 s2, s2, 2
	s_add_u32 s24, s37, s2
	v_ashrrev_i32_e32 v159, 31, v158
	s_addc_u32 s25, s38, 0
	v_lshlrev_b64 v[158:159], 2, v[158:159]
	v_lshl_add_u64 v[160:161], s[24:25], 0, v[158:159]
	v_lshl_add_u64 v[164:165], s[20:21], 0, v[158:159]
	v_lshlrev_b64 v[180:181], 2, v[134:135]
	global_load_dwordx4 v[172:175], v[160:161], off
	global_load_dwordx4 v[176:179], v[160:161], off offset:64
	global_load_dwordx4 v[182:185], v[160:161], off offset:512
	global_load_dwordx4 v[186:189], v[160:161], off offset:576
	v_lshl_add_u64 v[244:245], s[22:23], 0, v[158:159]
	v_lshl_add_u64 v[162:163], v[164:165], 0, v[180:181]
	global_load_dwordx4 v[190:193], v[162:163], off nt
	global_load_dwordx4 v[194:197], v[162:163], off offset:64 nt
	global_load_dwordx4 v[198:201], v[162:163], off offset:512 nt
	global_load_dwordx4 v[202:205], v[162:163], off offset:576 nt
	v_lshl_add_u64 v[240:241], v[164:165], 0, v[144:145]
	global_load_dwordx4 v[206:209], v[240:241], off nt
	global_load_dwordx4 v[210:213], v[240:241], off offset:64 nt
	global_load_dwordx4 v[214:217], v[240:241], off offset:512 nt
	global_load_dwordx4 v[218:221], v[240:241], off offset:576 nt
	v_lshl_add_u64 v[242:243], v[164:165], 0, v[146:147]
	global_load_dwordx4 v[222:225], v[242:243], off nt
	global_load_dwordx4 v[226:229], v[242:243], off offset:64 nt
	global_load_dwordx4 v[230:233], v[242:243], off offset:512 nt
	global_load_dwordx4 v[234:237], v[242:243], off offset:576 nt
	s_waitcnt vmcnt(8)
	v_pk_mul_f32 v[172:173], v[172:173], 0.5 op_sel_hi:[1,0]
	v_pk_mul_f32 v[174:175], v[174:175], 0.5 op_sel_hi:[1,0]
	v_pk_mul_f32 v[176:177], v[176:177], 0.5 op_sel_hi:[1,0]
	v_pk_mul_f32 v[178:179], v[178:179], 0.5 op_sel_hi:[1,0]
	v_pk_mul_f32 v[182:183], v[182:183], 0.5 op_sel_hi:[1,0]
	v_pk_mul_f32 v[184:185], v[184:185], 0.5 op_sel_hi:[1,0]
	v_pk_mul_f32 v[186:187], v[186:187], 0.5 op_sel_hi:[1,0]
	v_pk_mul_f32 v[188:189], v[188:189], 0.5 op_sel_hi:[1,0]
	v_lshl_add_u64 v[162:163], v[244:245], 0, v[180:181]
	v_pk_fma_f32 v[190:191], v[126:127], v[172:173], v[190:191]
	v_pk_fma_f32 v[192:193], v[128:129], v[174:175], v[192:193]
	v_pk_fma_f32 v[194:195], v[122:123], v[176:177], v[194:195]
	v_pk_fma_f32 v[196:197], v[124:125], v[178:179], v[196:197]
	v_pk_fma_f32 v[198:199], v[118:119], v[182:183], v[198:199]
	v_pk_fma_f32 v[200:201], v[120:121], v[184:185], v[200:201]
	v_pk_fma_f32 v[202:203], v[106:107], v[186:187], v[202:203]
	v_pk_fma_f32 v[204:205], v[108:109], v[188:189], v[204:205]
	global_store_dwordx4 v[162:163], v[190:193], off
	global_store_dwordx4 v[162:163], v[194:197], off offset:64
	global_store_dwordx4 v[162:163], v[198:201], off offset:512
	global_store_dwordx4 v[162:163], v[202:205], off offset:576
	v_lshl_add_u64 v[162:163], v[164:165], 0, v[148:149]
	global_load_dwordx4 v[190:193], v[162:163], off nt
	global_load_dwordx4 v[194:197], v[162:163], off offset:64 nt
	global_load_dwordx4 v[198:201], v[162:163], off offset:512 nt
	global_load_dwordx4 v[202:205], v[162:163], off offset:576 nt
	s_waitcnt vmcnt(12)
	v_lshl_add_u64 v[240:241], v[244:245], 0, v[144:145]
	v_pk_fma_f32 v[206:207], v[114:115], v[172:173], v[206:207]
	v_pk_fma_f32 v[208:209], v[116:117], v[174:175], v[208:209]
	v_pk_fma_f32 v[210:211], v[110:111], v[176:177], v[210:211]
	v_pk_fma_f32 v[212:213], v[112:113], v[178:179], v[212:213]
	v_pk_fma_f32 v[214:215], v[102:103], v[182:183], v[214:215]
	v_pk_fma_f32 v[216:217], v[104:105], v[184:185], v[216:217]
	v_pk_fma_f32 v[218:219], v[90:91], v[186:187], v[218:219]
	v_pk_fma_f32 v[220:221], v[92:93], v[188:189], v[220:221]
	global_store_dwordx4 v[240:241], v[206:209], off
	global_store_dwordx4 v[240:241], v[210:213], off offset:64
	global_store_dwordx4 v[240:241], v[214:217], off offset:512
	global_store_dwordx4 v[240:241], v[218:221], off offset:576
	v_lshl_add_u64 v[240:241], v[164:165], 0, v[150:151]
	global_load_dwordx4 v[206:209], v[240:241], off nt
	global_load_dwordx4 v[210:213], v[240:241], off offset:64 nt
	global_load_dwordx4 v[214:217], v[240:241], off offset:512 nt
	global_load_dwordx4 v[218:221], v[240:241], off offset:576 nt
	s_waitcnt vmcnt(16)
	v_lshl_add_u64 v[242:243], v[244:245], 0, v[146:147]
	v_pk_fma_f32 v[222:223], v[98:99], v[172:173], v[222:223]
	v_pk_fma_f32 v[224:225], v[100:101], v[174:175], v[224:225]
	v_pk_fma_f32 v[226:227], v[94:95], v[176:177], v[226:227]
	v_pk_fma_f32 v[228:229], v[96:97], v[178:179], v[228:229]
	v_pk_fma_f32 v[230:231], v[86:87], v[182:183], v[230:231]
	v_pk_fma_f32 v[232:233], v[88:89], v[184:185], v[232:233]
	v_pk_fma_f32 v[234:235], v[74:75], v[186:187], v[234:235]
	v_pk_fma_f32 v[236:237], v[76:77], v[188:189], v[236:237]
	global_store_dwordx4 v[242:243], v[222:225], off
	global_store_dwordx4 v[242:243], v[226:229], off offset:64
	global_store_dwordx4 v[242:243], v[230:233], off offset:512
	global_store_dwordx4 v[242:243], v[234:237], off offset:576
	v_lshl_add_u64 v[242:243], v[164:165], 0, v[152:153]
	global_load_dwordx4 v[222:225], v[242:243], off nt
	global_load_dwordx4 v[226:229], v[242:243], off offset:64 nt
	global_load_dwordx4 v[230:233], v[242:243], off offset:512 nt
	global_load_dwordx4 v[234:237], v[242:243], off offset:576 nt
	s_waitcnt vmcnt(16)
	v_lshl_add_u64 v[162:163], v[244:245], 0, v[148:149]
	v_pk_fma_f32 v[190:191], v[82:83], v[172:173], v[190:191]
	v_pk_fma_f32 v[192:193], v[84:85], v[174:175], v[192:193]
	v_pk_fma_f32 v[194:195], v[78:79], v[176:177], v[194:195]
	v_pk_fma_f32 v[196:197], v[80:81], v[178:179], v[196:197]
	v_pk_fma_f32 v[198:199], v[70:71], v[182:183], v[198:199]
	v_pk_fma_f32 v[200:201], v[72:73], v[184:185], v[200:201]
	v_pk_fma_f32 v[202:203], v[66:67], v[186:187], v[202:203]
	v_pk_fma_f32 v[204:205], v[68:69], v[188:189], v[204:205]
	global_store_dwordx4 v[162:163], v[190:193], off
	global_store_dwordx4 v[162:163], v[194:197], off offset:64
	global_store_dwordx4 v[162:163], v[198:201], off offset:512
	global_store_dwordx4 v[162:163], v[202:205], off offset:576
	v_lshl_add_u64 v[162:163], v[164:165], 0, v[154:155]
	global_load_dwordx4 v[190:193], v[162:163], off nt
	global_load_dwordx4 v[194:197], v[162:163], off offset:64 nt
	global_load_dwordx4 v[198:201], v[162:163], off offset:512 nt
	global_load_dwordx4 v[202:205], v[162:163], off offset:576 nt
	s_waitcnt vmcnt(16)
	v_lshl_add_u64 v[240:241], v[244:245], 0, v[150:151]
	v_pk_fma_f32 v[206:207], v[62:63], v[172:173], v[206:207]
	v_pk_fma_f32 v[208:209], v[64:65], v[174:175], v[208:209]
	v_pk_fma_f32 v[210:211], v[58:59], v[176:177], v[210:211]
	v_pk_fma_f32 v[212:213], v[60:61], v[178:179], v[212:213]
	v_pk_fma_f32 v[214:215], v[54:55], v[182:183], v[214:215]
	v_pk_fma_f32 v[216:217], v[56:57], v[184:185], v[216:217]
	v_pk_fma_f32 v[218:219], v[42:43], v[186:187], v[218:219]
	v_pk_fma_f32 v[220:221], v[44:45], v[188:189], v[220:221]
	global_store_dwordx4 v[240:241], v[206:209], off
	global_store_dwordx4 v[240:241], v[210:213], off offset:64
	global_store_dwordx4 v[240:241], v[214:217], off offset:512
	global_store_dwordx4 v[240:241], v[218:221], off offset:576
	v_lshl_add_u64 v[240:241], v[164:165], 0, v[156:157]
	global_load_dwordx4 v[206:209], v[240:241], off nt
	global_load_dwordx4 v[210:213], v[240:241], off offset:64 nt
	global_load_dwordx4 v[214:217], v[240:241], off offset:512 nt
	global_load_dwordx4 v[218:221], v[240:241], off offset:576 nt
	s_waitcnt vmcnt(16)
	v_lshl_add_u64 v[242:243], v[244:245], 0, v[152:153]
	v_pk_fma_f32 v[222:223], v[50:51], v[172:173], v[222:223]
	v_pk_fma_f32 v[224:225], v[52:53], v[174:175], v[224:225]
	v_pk_fma_f32 v[226:227], v[46:47], v[176:177], v[226:227]
	v_pk_fma_f32 v[228:229], v[48:49], v[178:179], v[228:229]
	v_pk_fma_f32 v[230:231], v[38:39], v[182:183], v[230:231]
	v_pk_fma_f32 v[232:233], v[40:41], v[184:185], v[232:233]
	v_pk_fma_f32 v[234:235], v[26:27], v[186:187], v[234:235]
	v_pk_fma_f32 v[236:237], v[28:29], v[188:189], v[236:237]
	global_store_dwordx4 v[242:243], v[222:225], off
	global_store_dwordx4 v[242:243], v[226:229], off offset:64
	global_store_dwordx4 v[242:243], v[230:233], off offset:512
	global_store_dwordx4 v[242:243], v[234:237], off offset:576
	s_waitcnt vmcnt(12)
	v_lshl_add_u64 v[162:163], v[244:245], 0, v[154:155]
	v_pk_fma_f32 v[190:191], v[34:35], v[172:173], v[190:191]
	v_pk_fma_f32 v[192:193], v[36:37], v[174:175], v[192:193]
	v_pk_fma_f32 v[194:195], v[30:31], v[176:177], v[194:195]
	v_pk_fma_f32 v[196:197], v[32:33], v[178:179], v[196:197]
	v_pk_fma_f32 v[198:199], v[22:23], v[182:183], v[198:199]
	v_pk_fma_f32 v[200:201], v[24:25], v[184:185], v[200:201]
	v_pk_fma_f32 v[202:203], v[10:11], v[186:187], v[202:203]
	v_pk_fma_f32 v[204:205], v[12:13], v[188:189], v[204:205]
	global_store_dwordx4 v[162:163], v[190:193], off
	global_store_dwordx4 v[162:163], v[194:197], off offset:64
	global_store_dwordx4 v[162:163], v[198:201], off offset:512
	global_store_dwordx4 v[162:163], v[202:205], off offset:576
	s_waitcnt vmcnt(8)
	v_lshl_add_u64 v[240:241], v[244:245], 0, v[156:157]
	v_pk_fma_f32 v[206:207], v[18:19], v[172:173], v[206:207]
	v_pk_fma_f32 v[208:209], v[20:21], v[174:175], v[208:209]
	v_pk_fma_f32 v[210:211], v[14:15], v[176:177], v[210:211]
	v_pk_fma_f32 v[212:213], v[16:17], v[178:179], v[212:213]
	v_pk_fma_f32 v[214:215], v[6:7], v[182:183], v[214:215]
	v_pk_fma_f32 v[216:217], v[8:9], v[184:185], v[216:217]
	v_pk_fma_f32 v[218:219], v[2:3], v[186:187], v[218:219]
	v_pk_fma_f32 v[220:221], v[4:5], v[188:189], v[220:221]
	global_store_dwordx4 v[240:241], v[206:209], off
	global_store_dwordx4 v[240:241], v[210:213], off offset:64
	global_store_dwordx4 v[240:241], v[214:217], off offset:512
	global_store_dwordx4 v[240:241], v[218:221], off offset:576
	s_and_b64 vcc, exec, s[4:5]
	s_mov_b64 s[4:5], -1
	v_readlane_b32 s54, v239, 19
	v_readlane_b32 s55, v239, 20
	v_readlane_b32 s58, v239, 23
	v_readlane_b32 s59, v239, 24
	v_readlane_b32 s60, v239, 25
	v_readlane_b32 s61, v239, 26
	v_readlane_b32 s62, v239, 27
	v_readlane_b32 s63, v239, 28
	v_readlane_b32 s64, v239, 29
	v_readlane_b32 s65, v239, 30
	v_readlane_b32 s66, v239, 31
	v_readlane_b32 s67, v239, 32
	s_cbranch_vccnz .LBB0_379
	s_andn2_b64 vcc, exec, s[12:13]
	s_cbranch_vccnz .LBB0_378
	s_barrier
	s_branch .LBB0_378

.LBB0_1104:
	s_add_i32 s2, s24, 0xffffff80
	s_ashr_i32 s17, s24, 31
	s_cmpk_lt_i32 s24, 0x80
	s_cselect_b32 s27, s17, 0
	s_cselect_b32 s26, s24, s2
	s_movk_i32 s19, 0x2400
	s_cselect_b32 s2, s87, s7
	s_cselect_b32 s17, s86, s6
	s_cselect_b32 s19, s19, 0x4800
	s_lshl_b64 s[26:27], s[26:27], 20
	s_add_u32 s26, s17, s26
	s_addc_u32 s27, s2, s27
	s_cmp_gt_i32 s24, 63
	s_cselect_b32 s2, s19, 0
	v_lshl_or_b32 v58, s25, 8, v177
	s_lshl_b32 s2, s2, 2
	s_add_u32 s24, s43, s2
	v_ashrrev_i32_e32 v59, 31, v58
	s_addc_u32 s25, s44, 0
	v_lshlrev_b64 v[174:175], 2, v[58:59]
	v_lshl_add_u64 v[58:59], s[24:25], 0, v[174:175]
	v_lshl_add_u64 v[174:175], s[26:27], 0, v[174:175]
	v_lshl_add_u64 v[186:187], v[174:175], 0, v[150:151]
	global_load_dwordx4 v[110:113], v[58:59], off
	global_load_dwordx4 v[114:117], v[58:59], off offset:64
	global_load_dwordx4 v[122:125], v[58:59], off offset:512
	global_load_dwordx4 v[182:185], v[58:59], off offset:576
	global_load_dwordx4 v[188:191], v[186:187], off nt
	global_load_dwordx4 v[192:195], v[186:187], off offset:64 nt
	global_load_dwordx4 v[196:199], v[186:187], off offset:512 nt
	global_load_dwordx4 v[200:203], v[186:187], off offset:576 nt
	v_lshl_add_u64 v[236:237], v[174:175], 0, v[160:161]
	global_load_dwordx4 v[204:207], v[236:237], off nt
	global_load_dwordx4 v[208:211], v[236:237], off offset:64 nt
	global_load_dwordx4 v[212:215], v[236:237], off offset:512 nt
	global_load_dwordx4 v[216:219], v[236:237], off offset:576 nt
	v_lshl_add_u64 v[240:241], v[174:175], 0, v[162:163]
	global_load_dwordx4 v[220:223], v[240:241], off nt
	global_load_dwordx4 v[224:227], v[240:241], off offset:64 nt
	global_load_dwordx4 v[228:231], v[240:241], off offset:512 nt
	global_load_dwordx4 v[232:235], v[240:241], off offset:576 nt
	s_waitcnt vmcnt(8)
	v_pk_fma_f32 v[188:189], v[142:143], v[110:111], v[188:189]
	v_pk_fma_f32 v[190:191], v[144:145], v[112:113], v[190:191]
	v_pk_fma_f32 v[192:193], v[138:139], v[114:115], v[192:193]
	v_pk_fma_f32 v[194:195], v[140:141], v[116:117], v[194:195]
	v_pk_fma_f32 v[196:197], v[134:135], v[122:123], v[196:197]
	v_pk_fma_f32 v[198:199], v[136:137], v[124:125], v[198:199]
	v_pk_fma_f32 v[200:201], v[126:127], v[182:183], v[200:201]
	v_pk_fma_f32 v[202:203], v[128:129], v[184:185], v[202:203]
	global_store_dwordx4 v[186:187], v[188:191], off
	global_store_dwordx4 v[186:187], v[192:195], off offset:64
	global_store_dwordx4 v[186:187], v[196:199], off offset:512
	global_store_dwordx4 v[186:187], v[200:203], off offset:576
	v_lshl_add_u64 v[60:61], v[174:175], 0, v[164:165]
	global_load_dwordx4 v[188:191], v[60:61], off nt
	global_load_dwordx4 v[192:195], v[60:61], off offset:64 nt
	global_load_dwordx4 v[196:199], v[60:61], off offset:512 nt
	global_load_dwordx4 v[200:203], v[60:61], off offset:576 nt
	s_waitcnt vmcnt(12)
	v_pk_fma_f32 v[204:205], v[130:131], v[110:111], v[204:205]
	v_pk_fma_f32 v[206:207], v[132:133], v[112:113], v[206:207]
	v_pk_fma_f32 v[208:209], v[118:119], v[114:115], v[208:209]
	v_pk_fma_f32 v[210:211], v[120:121], v[116:117], v[210:211]
	v_pk_fma_f32 v[212:213], v[106:107], v[122:123], v[212:213]
	v_pk_fma_f32 v[214:215], v[108:109], v[124:125], v[214:215]
	v_pk_fma_f32 v[216:217], v[98:99], v[182:183], v[216:217]
	v_pk_fma_f32 v[218:219], v[100:101], v[184:185], v[218:219]
	global_store_dwordx4 v[236:237], v[204:207], off
	global_store_dwordx4 v[236:237], v[208:211], off offset:64
	global_store_dwordx4 v[236:237], v[212:215], off offset:512
	global_store_dwordx4 v[236:237], v[216:219], off offset:576
	v_lshl_add_u64 v[236:237], v[174:175], 0, v[152:153]
	global_load_dwordx4 v[204:207], v[236:237], off nt
	global_load_dwordx4 v[208:211], v[236:237], off offset:64 nt
	global_load_dwordx4 v[212:215], v[236:237], off offset:512 nt
	global_load_dwordx4 v[216:219], v[236:237], off offset:576 nt
	s_waitcnt vmcnt(16)
	v_pk_fma_f32 v[220:221], v[102:103], v[110:111], v[220:221]
	v_pk_fma_f32 v[222:223], v[104:105], v[112:113], v[222:223]
	v_pk_fma_f32 v[224:225], v[94:95], v[114:115], v[224:225]
	v_pk_fma_f32 v[226:227], v[96:97], v[116:117], v[226:227]
	v_pk_fma_f32 v[228:229], v[90:91], v[122:123], v[228:229]
	v_pk_fma_f32 v[230:231], v[92:93], v[124:125], v[230:231]
	v_pk_fma_f32 v[232:233], v[82:83], v[182:183], v[232:233]
	v_pk_fma_f32 v[234:235], v[84:85], v[184:185], v[234:235]
	global_store_dwordx4 v[240:241], v[220:223], off
	global_store_dwordx4 v[240:241], v[224:227], off offset:64
	global_store_dwordx4 v[240:241], v[228:231], off offset:512
	global_store_dwordx4 v[240:241], v[232:235], off offset:576
	v_lshl_add_u64 v[240:241], v[174:175], 0, v[154:155]
	global_load_dwordx4 v[220:223], v[240:241], off nt
	global_load_dwordx4 v[224:227], v[240:241], off offset:64 nt
	global_load_dwordx4 v[228:231], v[240:241], off offset:512 nt
	global_load_dwordx4 v[232:235], v[240:241], off offset:576 nt
	s_waitcnt vmcnt(16)
	v_pk_fma_f32 v[188:189], v[86:87], v[110:111], v[188:189]
	v_pk_fma_f32 v[190:191], v[88:89], v[112:113], v[190:191]
	v_pk_fma_f32 v[192:193], v[78:79], v[114:115], v[192:193]
	v_pk_fma_f32 v[194:195], v[80:81], v[116:117], v[194:195]
	v_pk_fma_f32 v[196:197], v[74:75], v[122:123], v[196:197]
	v_pk_fma_f32 v[198:199], v[76:77], v[124:125], v[198:199]
	v_pk_fma_f32 v[200:201], v[70:71], v[182:183], v[200:201]
	v_pk_fma_f32 v[202:203], v[72:73], v[184:185], v[202:203]
	global_store_dwordx4 v[60:61], v[188:191], off
	global_store_dwordx4 v[60:61], v[192:195], off offset:64
	global_store_dwordx4 v[60:61], v[196:199], off offset:512
	global_store_dwordx4 v[60:61], v[200:203], off offset:576
	v_lshl_add_u64 v[60:61], v[174:175], 0, v[156:157]
	global_load_dwordx4 v[188:191], v[60:61], off nt
	global_load_dwordx4 v[192:195], v[60:61], off offset:64 nt
	global_load_dwordx4 v[196:199], v[60:61], off offset:512 nt
	global_load_dwordx4 v[200:203], v[60:61], off offset:576 nt
	s_waitcnt vmcnt(16)
	v_pk_fma_f32 v[204:205], v[66:67], v[110:111], v[204:205]
	v_pk_fma_f32 v[206:207], v[68:69], v[112:113], v[206:207]
	v_pk_fma_f32 v[208:209], v[62:63], v[114:115], v[208:209]
	v_pk_fma_f32 v[210:211], v[64:65], v[116:117], v[210:211]
	v_pk_fma_f32 v[212:213], v[54:55], v[122:123], v[212:213]
	v_pk_fma_f32 v[214:215], v[56:57], v[124:125], v[214:215]
	v_pk_fma_f32 v[216:217], v[50:51], v[182:183], v[216:217]
	v_pk_fma_f32 v[218:219], v[52:53], v[184:185], v[218:219]
	global_store_dwordx4 v[236:237], v[204:207], off
	global_store_dwordx4 v[236:237], v[208:211], off offset:64
	global_store_dwordx4 v[236:237], v[212:215], off offset:512
	global_store_dwordx4 v[236:237], v[216:219], off offset:576
	v_lshl_add_u64 v[236:237], v[174:175], 0, v[158:159]
	global_load_dwordx4 v[204:207], v[236:237], off nt
	global_load_dwordx4 v[208:211], v[236:237], off offset:64 nt
	global_load_dwordx4 v[212:215], v[236:237], off offset:512 nt
	global_load_dwordx4 v[216:219], v[236:237], off offset:576 nt
	s_waitcnt vmcnt(16)
	v_pk_fma_f32 v[220:221], v[46:47], v[110:111], v[220:221]
	v_pk_fma_f32 v[222:223], v[48:49], v[112:113], v[222:223]
	v_pk_fma_f32 v[224:225], v[42:43], v[114:115], v[224:225]
	v_pk_fma_f32 v[226:227], v[44:45], v[116:117], v[226:227]
	v_pk_fma_f32 v[228:229], v[38:39], v[122:123], v[228:229]
	v_pk_fma_f32 v[230:231], v[40:41], v[124:125], v[230:231]
	v_pk_fma_f32 v[232:233], v[34:35], v[182:183], v[232:233]
	v_pk_fma_f32 v[234:235], v[36:37], v[184:185], v[234:235]
	global_store_dwordx4 v[240:241], v[220:223], off
	global_store_dwordx4 v[240:241], v[224:227], off offset:64
	global_store_dwordx4 v[240:241], v[228:231], off offset:512
	global_store_dwordx4 v[240:241], v[232:235], off offset:576
	s_waitcnt vmcnt(12)
	v_pk_fma_f32 v[188:189], v[30:31], v[110:111], v[188:189]
	v_pk_fma_f32 v[190:191], v[32:33], v[112:113], v[190:191]
	v_pk_fma_f32 v[192:193], v[26:27], v[114:115], v[192:193]
	v_pk_fma_f32 v[194:195], v[28:29], v[116:117], v[194:195]
	v_pk_fma_f32 v[196:197], v[22:23], v[122:123], v[196:197]
	v_pk_fma_f32 v[198:199], v[24:25], v[124:125], v[198:199]
	v_pk_fma_f32 v[200:201], v[18:19], v[182:183], v[200:201]
	v_pk_fma_f32 v[202:203], v[20:21], v[184:185], v[202:203]
	global_store_dwordx4 v[60:61], v[188:191], off
	global_store_dwordx4 v[60:61], v[192:195], off offset:64
	global_store_dwordx4 v[60:61], v[196:199], off offset:512
	global_store_dwordx4 v[60:61], v[200:203], off offset:576
	s_waitcnt vmcnt(8)
	v_pk_fma_f32 v[204:205], v[14:15], v[110:111], v[204:205]
	v_pk_fma_f32 v[206:207], v[16:17], v[112:113], v[206:207]
	v_pk_fma_f32 v[208:209], v[10:11], v[114:115], v[208:209]
	v_pk_fma_f32 v[210:211], v[12:13], v[116:117], v[210:211]
	v_pk_fma_f32 v[212:213], v[6:7], v[122:123], v[212:213]
	v_pk_fma_f32 v[214:215], v[8:9], v[124:125], v[214:215]
	v_pk_fma_f32 v[216:217], v[2:3], v[182:183], v[216:217]
	v_pk_fma_f32 v[218:219], v[4:5], v[184:185], v[218:219]
	global_store_dwordx4 v[236:237], v[204:207], off
	global_store_dwordx4 v[236:237], v[208:211], off offset:64
	global_store_dwordx4 v[236:237], v[212:215], off offset:512
	global_store_dwordx4 v[236:237], v[216:219], off offset:576
	s_mov_b64 s[24:25], -1
	s_andn2_b64 vcc, exec, s[4:5]
	s_cbranch_vccnz .LBB0_1093
	s_andn2_b64 vcc, exec, s[10:11]
	s_cbranch_vccnz .LBB0_1092
	s_barrier
	s_branch .LBB0_1092

.LBB0_1370:
	s_add_i32 s2, s47, 0xffffff80
	s_ashr_i32 s20, s47, 31
	s_cmpk_lt_i32 s47, 0x80
	s_cselect_b32 s21, s20, 0
	s_cselect_b32 s20, s47, s2
	s_movk_i32 s23, 0x2400
	s_cselect_b32 s2, s87, s9
	s_cselect_b32 s22, s86, s8
	s_cselect_b32 s23, s23, 0x4800
	s_lshl_b64 s[20:21], s[20:21], 20
	s_add_u32 s20, s22, s20
	s_addc_u32 s21, s2, s21
	s_cmp_gt_i32 s47, 63
	s_cselect_b32 s2, s23, 0
	v_lshl_or_b32 v158, s48, 8, v177
	s_lshl_b32 s2, s2, 2
	s_add_u32 s22, s37, s2
	v_ashrrev_i32_e32 v159, 31, v158
	s_addc_u32 s23, s38, 0
	v_lshlrev_b64 v[174:175], 2, v[158:159]
	v_lshl_add_u64 v[182:183], s[22:23], 0, v[174:175]
	global_load_dwordx4 v[158:161], v[182:183], off
	global_load_dwordx4 v[162:165], v[182:183], off offset:64
	global_load_dwordx4 v[166:169], v[182:183], off offset:512
	global_load_dwordx4 v[170:173], v[182:183], off offset:576
	v_lshl_add_u64 v[240:241], s[20:21], 0, v[174:175]
	v_lshl_add_u64 v[232:233], v[240:241], 0, v[134:135]
	global_load_dwordx4 v[184:187], v[232:233], off nt
	global_load_dwordx4 v[188:191], v[232:233], off offset:64 nt
	global_load_dwordx4 v[192:195], v[232:233], off offset:512 nt
	global_load_dwordx4 v[196:199], v[232:233], off offset:576 nt
	v_lshl_add_u64 v[234:235], v[240:241], 0, v[144:145]
	global_load_dwordx4 v[200:203], v[234:235], off nt
	global_load_dwordx4 v[204:207], v[234:235], off offset:64 nt
	global_load_dwordx4 v[208:211], v[234:235], off offset:512 nt
	global_load_dwordx4 v[212:215], v[234:235], off offset:576 nt
	v_lshl_add_u64 v[236:237], v[240:241], 0, v[146:147]
	global_load_dwordx4 v[216:219], v[236:237], off nt
	global_load_dwordx4 v[220:223], v[236:237], off offset:64 nt
	global_load_dwordx4 v[224:227], v[236:237], off offset:512 nt
	global_load_dwordx4 v[228:231], v[236:237], off offset:576 nt
	s_waitcnt vmcnt(8)
	v_pk_mul_f32 v[158:159], v[158:159], 0.5 op_sel_hi:[1,0]
	v_pk_mul_f32 v[160:161], v[160:161], 0.5 op_sel_hi:[1,0]
	v_pk_mul_f32 v[162:163], v[162:163], 0.5 op_sel_hi:[1,0]
	v_pk_mul_f32 v[164:165], v[164:165], 0.5 op_sel_hi:[1,0]
	v_pk_mul_f32 v[166:167], v[166:167], 0.5 op_sel_hi:[1,0]
	v_pk_mul_f32 v[168:169], v[168:169], 0.5 op_sel_hi:[1,0]
	v_pk_mul_f32 v[170:171], v[170:171], 0.5 op_sel_hi:[1,0]
	v_pk_mul_f32 v[172:173], v[172:173], 0.5 op_sel_hi:[1,0]
	v_pk_fma_f32 v[184:185], v[126:127], v[158:159], v[184:185]
	v_pk_fma_f32 v[186:187], v[128:129], v[160:161], v[186:187]
	v_pk_fma_f32 v[188:189], v[122:123], v[162:163], v[188:189]
	v_pk_fma_f32 v[190:191], v[124:125], v[164:165], v[190:191]
	v_pk_fma_f32 v[192:193], v[118:119], v[166:167], v[192:193]
	v_pk_fma_f32 v[194:195], v[120:121], v[168:169], v[194:195]
	v_pk_fma_f32 v[196:197], v[110:111], v[170:171], v[196:197]
	v_pk_fma_f32 v[198:199], v[112:113], v[172:173], v[198:199]
	global_store_dwordx4 v[232:233], v[184:187], off
	global_store_dwordx4 v[232:233], v[188:191], off offset:64
	global_store_dwordx4 v[232:233], v[192:195], off offset:512
	global_store_dwordx4 v[232:233], v[196:199], off offset:576
	v_lshl_add_u64 v[232:233], v[240:241], 0, v[148:149]
	global_load_dwordx4 v[184:187], v[232:233], off nt
	global_load_dwordx4 v[188:191], v[232:233], off offset:64 nt
	global_load_dwordx4 v[192:195], v[232:233], off offset:512 nt
	global_load_dwordx4 v[196:199], v[232:233], off offset:576 nt
	s_waitcnt vmcnt(12)
	v_pk_fma_f32 v[200:201], v[114:115], v[158:159], v[200:201]
	v_pk_fma_f32 v[202:203], v[116:117], v[160:161], v[202:203]
	v_pk_fma_f32 v[204:205], v[106:107], v[162:163], v[204:205]
	v_pk_fma_f32 v[206:207], v[108:109], v[164:165], v[206:207]
	v_pk_fma_f32 v[208:209], v[102:103], v[166:167], v[208:209]
	v_pk_fma_f32 v[210:211], v[104:105], v[168:169], v[210:211]
	v_pk_fma_f32 v[212:213], v[94:95], v[170:171], v[212:213]
	v_pk_fma_f32 v[214:215], v[96:97], v[172:173], v[214:215]
	global_store_dwordx4 v[234:235], v[200:203], off
	global_store_dwordx4 v[234:235], v[204:207], off offset:64
	global_store_dwordx4 v[234:235], v[208:211], off offset:512
	global_store_dwordx4 v[234:235], v[212:215], off offset:576
	v_lshl_add_u64 v[234:235], v[240:241], 0, v[136:137]
	global_load_dwordx4 v[200:203], v[234:235], off nt
	global_load_dwordx4 v[204:207], v[234:235], off offset:64 nt
	global_load_dwordx4 v[208:211], v[234:235], off offset:512 nt
	global_load_dwordx4 v[212:215], v[234:235], off offset:576 nt
	s_waitcnt vmcnt(16)
	v_pk_fma_f32 v[216:217], v[98:99], v[158:159], v[216:217]
	v_pk_fma_f32 v[218:219], v[100:101], v[160:161], v[218:219]
	v_pk_fma_f32 v[220:221], v[90:91], v[162:163], v[220:221]
	v_pk_fma_f32 v[222:223], v[92:93], v[164:165], v[222:223]
	v_pk_fma_f32 v[224:225], v[86:87], v[166:167], v[224:225]
	v_pk_fma_f32 v[226:227], v[88:89], v[168:169], v[226:227]
	v_pk_fma_f32 v[228:229], v[82:83], v[170:171], v[228:229]
	v_pk_fma_f32 v[230:231], v[84:85], v[172:173], v[230:231]
	global_store_dwordx4 v[236:237], v[216:219], off
	global_store_dwordx4 v[236:237], v[220:223], off offset:64
	global_store_dwordx4 v[236:237], v[224:227], off offset:512
	global_store_dwordx4 v[236:237], v[228:231], off offset:576
	v_lshl_add_u64 v[236:237], v[240:241], 0, v[138:139]
	global_load_dwordx4 v[216:219], v[236:237], off nt
	global_load_dwordx4 v[220:223], v[236:237], off offset:64 nt
	global_load_dwordx4 v[224:227], v[236:237], off offset:512 nt
	global_load_dwordx4 v[228:231], v[236:237], off offset:576 nt
	s_waitcnt vmcnt(16)
	v_pk_fma_f32 v[184:185], v[78:79], v[158:159], v[184:185]
	v_pk_fma_f32 v[186:187], v[80:81], v[160:161], v[186:187]
	v_pk_fma_f32 v[188:189], v[74:75], v[162:163], v[188:189]
	v_pk_fma_f32 v[190:191], v[76:77], v[164:165], v[190:191]
	v_pk_fma_f32 v[192:193], v[70:71], v[166:167], v[192:193]
	v_pk_fma_f32 v[194:195], v[72:73], v[168:169], v[194:195]
	v_pk_fma_f32 v[196:197], v[66:67], v[170:171], v[196:197]
	v_pk_fma_f32 v[198:199], v[68:69], v[172:173], v[198:199]
	global_store_dwordx4 v[232:233], v[184:187], off
	global_store_dwordx4 v[232:233], v[188:191], off offset:64
	global_store_dwordx4 v[232:233], v[192:195], off offset:512
	global_store_dwordx4 v[232:233], v[196:199], off offset:576
	v_lshl_add_u64 v[232:233], v[240:241], 0, v[140:141]
	global_load_dwordx4 v[184:187], v[232:233], off nt
	global_load_dwordx4 v[188:191], v[232:233], off offset:64 nt
	global_load_dwordx4 v[192:195], v[232:233], off offset:512 nt
	global_load_dwordx4 v[196:199], v[232:233], off offset:576 nt
	s_waitcnt vmcnt(16)
	v_pk_fma_f32 v[200:201], v[62:63], v[158:159], v[200:201]
	v_pk_fma_f32 v[202:203], v[64:65], v[160:161], v[202:203]
	v_pk_fma_f32 v[204:205], v[58:59], v[162:163], v[204:205]
	v_pk_fma_f32 v[206:207], v[60:61], v[164:165], v[206:207]
	v_pk_fma_f32 v[208:209], v[54:55], v[166:167], v[208:209]
	v_pk_fma_f32 v[210:211], v[56:57], v[168:169], v[210:211]
	v_pk_fma_f32 v[212:213], v[50:51], v[170:171], v[212:213]
	v_pk_fma_f32 v[214:215], v[52:53], v[172:173], v[214:215]
	global_store_dwordx4 v[234:235], v[200:203], off
	global_store_dwordx4 v[234:235], v[204:207], off offset:64
	global_store_dwordx4 v[234:235], v[208:211], off offset:512
	global_store_dwordx4 v[234:235], v[212:215], off offset:576
	v_lshl_add_u64 v[234:235], v[240:241], 0, v[142:143]
	global_load_dwordx4 v[200:203], v[234:235], off nt
	global_load_dwordx4 v[204:207], v[234:235], off offset:64 nt
	global_load_dwordx4 v[208:211], v[234:235], off offset:512 nt
	global_load_dwordx4 v[212:215], v[234:235], off offset:576 nt
	s_waitcnt vmcnt(16)
	v_pk_fma_f32 v[216:217], v[46:47], v[158:159], v[216:217]
	v_pk_fma_f32 v[218:219], v[48:49], v[160:161], v[218:219]
	v_pk_fma_f32 v[220:221], v[42:43], v[162:163], v[220:221]
	v_pk_fma_f32 v[222:223], v[44:45], v[164:165], v[222:223]
	v_pk_fma_f32 v[224:225], v[38:39], v[166:167], v[224:225]
	v_pk_fma_f32 v[226:227], v[40:41], v[168:169], v[226:227]
	v_pk_fma_f32 v[228:229], v[34:35], v[170:171], v[228:229]
	v_pk_fma_f32 v[230:231], v[36:37], v[172:173], v[230:231]
	global_store_dwordx4 v[236:237], v[216:219], off
	global_store_dwordx4 v[236:237], v[220:223], off offset:64
	global_store_dwordx4 v[236:237], v[224:227], off offset:512
	global_store_dwordx4 v[236:237], v[228:231], off offset:576
	s_waitcnt vmcnt(12)
	v_pk_fma_f32 v[184:185], v[30:31], v[158:159], v[184:185]
	v_pk_fma_f32 v[186:187], v[32:33], v[160:161], v[186:187]
	v_pk_fma_f32 v[188:189], v[26:27], v[162:163], v[188:189]
	v_pk_fma_f32 v[190:191], v[28:29], v[164:165], v[190:191]
	v_pk_fma_f32 v[192:193], v[22:23], v[166:167], v[192:193]
	v_pk_fma_f32 v[194:195], v[24:25], v[168:169], v[194:195]
	v_pk_fma_f32 v[196:197], v[18:19], v[170:171], v[196:197]
	v_pk_fma_f32 v[198:199], v[20:21], v[172:173], v[198:199]
	global_store_dwordx4 v[232:233], v[184:187], off
	global_store_dwordx4 v[232:233], v[188:191], off offset:64
	global_store_dwordx4 v[232:233], v[192:195], off offset:512
	global_store_dwordx4 v[232:233], v[196:199], off offset:576
	s_waitcnt vmcnt(8)
	v_pk_fma_f32 v[200:201], v[14:15], v[158:159], v[200:201]
	v_pk_fma_f32 v[202:203], v[16:17], v[160:161], v[202:203]
	v_pk_fma_f32 v[204:205], v[10:11], v[162:163], v[204:205]
	v_pk_fma_f32 v[206:207], v[12:13], v[164:165], v[206:207]
	v_pk_fma_f32 v[208:209], v[6:7], v[166:167], v[208:209]
	v_pk_fma_f32 v[210:211], v[8:9], v[168:169], v[210:211]
	v_pk_fma_f32 v[212:213], v[2:3], v[170:171], v[212:213]
	v_pk_fma_f32 v[214:215], v[4:5], v[172:173], v[214:215]
	global_store_dwordx4 v[234:235], v[200:203], off
	global_store_dwordx4 v[234:235], v[204:207], off offset:64
	global_store_dwordx4 v[234:235], v[208:211], off offset:512
	global_store_dwordx4 v[234:235], v[212:215], off offset:576
	s_mov_b64 s[20:21], -1
	s_and_b64 vcc, exec, s[4:5]
	s_cbranch_vccnz .LBB0_1355
	s_andn2_b64 vcc, exec, s[12:13]
	s_cbranch_vccnz .LBB0_1354
	s_barrier
	s_branch .LBB0_1354

.LBB0_2331:
	s_add_i32 s2, s20, 0xffffff80
	s_ashr_i32 s13, s20, 31
	s_cmpk_lt_i32 s20, 0x80
	s_cselect_b32 s23, s13, 0
	s_cselect_b32 s22, s20, s2
	s_cselect_b32 s2, s87, s42
	s_cselect_b32 s13, s86, s41
	s_cselect_b32 s15, s51, 0x4800
	s_lshl_b64 s[22:23], s[22:23], 20
	s_add_u32 s22, s13, s22
	s_addc_u32 s23, s2, s23
	s_cmp_gt_i32 s20, 63
	s_cselect_b32 s2, s15, 0
	v_lshl_or_b32 v86, s21, 8, v177
	s_lshl_b32 s2, s2, 2
	s_add_u32 s20, s43, s2
	v_ashrrev_i32_e32 v87, 31, v86
	s_addc_u32 s21, s44, 0
	v_lshlrev_b64 v[174:175], 2, v[86:87]
	v_lshl_add_u64 v[86:87], s[20:21], 0, v[174:175]
	v_lshl_add_u64 v[174:175], s[22:23], 0, v[174:175]
	v_lshl_add_u64 v[186:187], v[174:175], 0, v[150:151]
	global_load_dwordx4 v[126:129], v[86:87], off
	global_load_dwordx4 v[130:133], v[86:87], off offset:64
	global_load_dwordx4 v[138:141], v[86:87], off offset:512
	global_load_dwordx4 v[182:185], v[86:87], off offset:576
	global_load_dwordx4 v[188:191], v[186:187], off nt
	global_load_dwordx4 v[192:195], v[186:187], off offset:64 nt
	global_load_dwordx4 v[196:199], v[186:187], off offset:512 nt
	global_load_dwordx4 v[200:203], v[186:187], off offset:576 nt
	v_lshl_add_u64 v[236:237], v[174:175], 0, v[160:161]
	global_load_dwordx4 v[204:207], v[236:237], off nt
	global_load_dwordx4 v[208:211], v[236:237], off offset:64 nt
	global_load_dwordx4 v[212:215], v[236:237], off offset:512 nt
	global_load_dwordx4 v[216:219], v[236:237], off offset:576 nt
	v_lshl_add_u64 v[240:241], v[174:175], 0, v[162:163]
	global_load_dwordx4 v[220:223], v[240:241], off nt
	global_load_dwordx4 v[224:227], v[240:241], off offset:64 nt
	global_load_dwordx4 v[228:231], v[240:241], off offset:512 nt
	global_load_dwordx4 v[232:235], v[240:241], off offset:576 nt
	s_waitcnt vmcnt(8)
	v_pk_fma_f32 v[188:189], v[142:143], v[126:127], v[188:189]
	v_pk_fma_f32 v[190:191], v[144:145], v[128:129], v[190:191]
	v_pk_fma_f32 v[192:193], v[134:135], v[130:131], v[192:193]
	v_pk_fma_f32 v[194:195], v[136:137], v[132:133], v[194:195]
	v_pk_fma_f32 v[196:197], v[122:123], v[138:139], v[196:197]
	v_pk_fma_f32 v[198:199], v[124:125], v[140:141], v[198:199]
	v_pk_fma_f32 v[200:201], v[114:115], v[182:183], v[200:201]
	v_pk_fma_f32 v[202:203], v[116:117], v[184:185], v[202:203]
	global_store_dwordx4 v[186:187], v[188:191], off
	global_store_dwordx4 v[186:187], v[192:195], off offset:64
	global_store_dwordx4 v[186:187], v[196:199], off offset:512
	global_store_dwordx4 v[186:187], v[200:203], off offset:576
	v_lshl_add_u64 v[88:89], v[174:175], 0, v[164:165]
	global_load_dwordx4 v[188:191], v[88:89], off nt
	global_load_dwordx4 v[192:195], v[88:89], off offset:64 nt
	global_load_dwordx4 v[196:199], v[88:89], off offset:512 nt
	global_load_dwordx4 v[200:203], v[88:89], off offset:576 nt
	s_waitcnt vmcnt(12)
	v_pk_fma_f32 v[204:205], v[118:119], v[126:127], v[204:205]
	v_pk_fma_f32 v[206:207], v[120:121], v[128:129], v[206:207]
	v_pk_fma_f32 v[208:209], v[110:111], v[130:131], v[208:209]
	v_pk_fma_f32 v[210:211], v[112:113], v[132:133], v[210:211]
	v_pk_fma_f32 v[212:213], v[106:107], v[138:139], v[212:213]
	v_pk_fma_f32 v[214:215], v[108:109], v[140:141], v[214:215]
	v_pk_fma_f32 v[216:217], v[98:99], v[182:183], v[216:217]
	v_pk_fma_f32 v[218:219], v[100:101], v[184:185], v[218:219]
	global_store_dwordx4 v[236:237], v[204:207], off
	global_store_dwordx4 v[236:237], v[208:211], off offset:64
	global_store_dwordx4 v[236:237], v[212:215], off offset:512
	global_store_dwordx4 v[236:237], v[216:219], off offset:576
	v_lshl_add_u64 v[236:237], v[174:175], 0, v[152:153]
	global_load_dwordx4 v[204:207], v[236:237], off nt
	global_load_dwordx4 v[208:211], v[236:237], off offset:64 nt
	global_load_dwordx4 v[212:215], v[236:237], off offset:512 nt
	global_load_dwordx4 v[216:219], v[236:237], off offset:576 nt
	s_waitcnt vmcnt(16)
	v_pk_fma_f32 v[220:221], v[102:103], v[126:127], v[220:221]
	v_pk_fma_f32 v[222:223], v[104:105], v[128:129], v[222:223]
	v_pk_fma_f32 v[224:225], v[94:95], v[130:131], v[224:225]
	v_pk_fma_f32 v[226:227], v[96:97], v[132:133], v[226:227]
	v_pk_fma_f32 v[228:229], v[90:91], v[138:139], v[228:229]
	v_pk_fma_f32 v[230:231], v[92:93], v[140:141], v[230:231]
	v_pk_fma_f32 v[232:233], v[78:79], v[182:183], v[232:233]
	v_pk_fma_f32 v[234:235], v[80:81], v[184:185], v[234:235]
	global_store_dwordx4 v[240:241], v[220:223], off
	global_store_dwordx4 v[240:241], v[224:227], off offset:64
	global_store_dwordx4 v[240:241], v[228:231], off offset:512
	global_store_dwordx4 v[240:241], v[232:235], off offset:576
	v_lshl_add_u64 v[240:241], v[174:175], 0, v[154:155]
	global_load_dwordx4 v[220:223], v[240:241], off nt
	global_load_dwordx4 v[224:227], v[240:241], off offset:64 nt
	global_load_dwordx4 v[228:231], v[240:241], off offset:512 nt
	global_load_dwordx4 v[232:235], v[240:241], off offset:576 nt
	s_waitcnt vmcnt(16)
	v_pk_fma_f32 v[188:189], v[82:83], v[126:127], v[188:189]
	v_pk_fma_f32 v[190:191], v[84:85], v[128:129], v[190:191]
	v_pk_fma_f32 v[192:193], v[74:75], v[130:131], v[192:193]
	v_pk_fma_f32 v[194:195], v[76:77], v[132:133], v[194:195]
	v_pk_fma_f32 v[196:197], v[70:71], v[138:139], v[196:197]
	v_pk_fma_f32 v[198:199], v[72:73], v[140:141], v[198:199]
	v_pk_fma_f32 v[200:201], v[66:67], v[182:183], v[200:201]
	v_pk_fma_f32 v[202:203], v[68:69], v[184:185], v[202:203]
	global_store_dwordx4 v[88:89], v[188:191], off
	global_store_dwordx4 v[88:89], v[192:195], off offset:64
	global_store_dwordx4 v[88:89], v[196:199], off offset:512
	global_store_dwordx4 v[88:89], v[200:203], off offset:576
	v_lshl_add_u64 v[88:89], v[174:175], 0, v[156:157]
	global_load_dwordx4 v[188:191], v[88:89], off nt
	global_load_dwordx4 v[192:195], v[88:89], off offset:64 nt
	global_load_dwordx4 v[196:199], v[88:89], off offset:512 nt
	global_load_dwordx4 v[200:203], v[88:89], off offset:576 nt
	s_waitcnt vmcnt(16)
	v_pk_fma_f32 v[204:205], v[62:63], v[126:127], v[204:205]
	v_pk_fma_f32 v[206:207], v[64:65], v[128:129], v[206:207]
	v_pk_fma_f32 v[208:209], v[58:59], v[130:131], v[208:209]
	v_pk_fma_f32 v[210:211], v[60:61], v[132:133], v[210:211]
	v_pk_fma_f32 v[212:213], v[54:55], v[138:139], v[212:213]
	v_pk_fma_f32 v[214:215], v[56:57], v[140:141], v[214:215]
	v_pk_fma_f32 v[216:217], v[50:51], v[182:183], v[216:217]
	v_pk_fma_f32 v[218:219], v[52:53], v[184:185], v[218:219]
	global_store_dwordx4 v[236:237], v[204:207], off
	global_store_dwordx4 v[236:237], v[208:211], off offset:64
	global_store_dwordx4 v[236:237], v[212:215], off offset:512
	global_store_dwordx4 v[236:237], v[216:219], off offset:576
	v_lshl_add_u64 v[236:237], v[174:175], 0, v[158:159]
	global_load_dwordx4 v[204:207], v[236:237], off nt
	global_load_dwordx4 v[208:211], v[236:237], off offset:64 nt
	global_load_dwordx4 v[212:215], v[236:237], off offset:512 nt
	global_load_dwordx4 v[216:219], v[236:237], off offset:576 nt
	s_waitcnt vmcnt(16)
	v_pk_fma_f32 v[220:221], v[46:47], v[126:127], v[220:221]
	v_pk_fma_f32 v[222:223], v[48:49], v[128:129], v[222:223]
	v_pk_fma_f32 v[224:225], v[42:43], v[130:131], v[224:225]
	v_pk_fma_f32 v[226:227], v[44:45], v[132:133], v[226:227]
	v_pk_fma_f32 v[228:229], v[38:39], v[138:139], v[228:229]
	v_pk_fma_f32 v[230:231], v[40:41], v[140:141], v[230:231]
	v_pk_fma_f32 v[232:233], v[34:35], v[182:183], v[232:233]
	v_pk_fma_f32 v[234:235], v[36:37], v[184:185], v[234:235]
	global_store_dwordx4 v[240:241], v[220:223], off
	global_store_dwordx4 v[240:241], v[224:227], off offset:64
	global_store_dwordx4 v[240:241], v[228:231], off offset:512
	global_store_dwordx4 v[240:241], v[232:235], off offset:576
	s_waitcnt vmcnt(12)
	v_pk_fma_f32 v[188:189], v[30:31], v[126:127], v[188:189]
	v_pk_fma_f32 v[190:191], v[32:33], v[128:129], v[190:191]
	v_pk_fma_f32 v[192:193], v[26:27], v[130:131], v[192:193]
	v_pk_fma_f32 v[194:195], v[28:29], v[132:133], v[194:195]
	v_pk_fma_f32 v[196:197], v[22:23], v[138:139], v[196:197]
	v_pk_fma_f32 v[198:199], v[24:25], v[140:141], v[198:199]
	v_pk_fma_f32 v[200:201], v[14:15], v[182:183], v[200:201]
	v_pk_fma_f32 v[202:203], v[16:17], v[184:185], v[202:203]
	global_store_dwordx4 v[88:89], v[188:191], off
	global_store_dwordx4 v[88:89], v[192:195], off offset:64
	global_store_dwordx4 v[88:89], v[196:199], off offset:512
	global_store_dwordx4 v[88:89], v[200:203], off offset:576
	s_waitcnt vmcnt(8)
	v_pk_fma_f32 v[204:205], v[18:19], v[126:127], v[204:205]
	v_pk_fma_f32 v[206:207], v[20:21], v[128:129], v[206:207]
	v_pk_fma_f32 v[208:209], v[10:11], v[130:131], v[208:209]
	v_pk_fma_f32 v[210:211], v[12:13], v[132:133], v[210:211]
	v_pk_fma_f32 v[212:213], v[6:7], v[138:139], v[212:213]
	v_pk_fma_f32 v[214:215], v[8:9], v[140:141], v[214:215]
	v_pk_fma_f32 v[216:217], v[2:3], v[182:183], v[216:217]
	v_pk_fma_f32 v[218:219], v[4:5], v[184:185], v[218:219]
	global_store_dwordx4 v[236:237], v[204:207], off
	global_store_dwordx4 v[236:237], v[208:211], off offset:64
	global_store_dwordx4 v[236:237], v[212:215], off offset:512
	global_store_dwordx4 v[236:237], v[216:219], off offset:576
	s_mov_b64 s[20:21], -1
	s_andn2_b64 vcc, exec, s[4:5]
	s_cbranch_vccnz .LBB0_2320
	s_andn2_b64 vcc, exec, s[6:7]
	s_cbranch_vccnz .LBB0_2319
	s_barrier
	s_branch .LBB0_2319

.LBB0_2586:
	s_add_i32 s2, s48, 0xffffff80
	s_ashr_i32 s16, s48, 31
	s_cmpk_lt_i32 s48, 0x80
	s_cselect_b32 s17, s16, 0
	s_cselect_b32 s16, s48, s2
	s_cselect_b32 s2, s87, s36
	s_cselect_b32 s18, s86, s35
	s_cselect_b32 s19, s45, 0x4800
	s_lshl_b64 s[16:17], s[16:17], 20
	s_add_u32 s16, s18, s16
	s_addc_u32 s17, s2, s17
	s_cmp_gt_i32 s48, 63
	s_cselect_b32 s2, s19, 0
	v_lshl_or_b32 v158, s49, 8, v177
	s_lshl_b32 s2, s2, 2
	s_add_u32 s18, s37, s2
	v_ashrrev_i32_e32 v159, 31, v158
	s_addc_u32 s19, s38, 0
	v_lshlrev_b64 v[174:175], 2, v[158:159]
	v_lshl_add_u64 v[182:183], s[18:19], 0, v[174:175]
	global_load_dwordx4 v[158:161], v[182:183], off
	global_load_dwordx4 v[162:165], v[182:183], off offset:64
	global_load_dwordx4 v[166:169], v[182:183], off offset:512
	global_load_dwordx4 v[170:173], v[182:183], off offset:576
	v_lshl_add_u64 v[240:241], s[16:17], 0, v[174:175]
	v_lshl_add_u64 v[232:233], v[240:241], 0, v[134:135]
	global_load_dwordx4 v[184:187], v[232:233], off nt
	global_load_dwordx4 v[188:191], v[232:233], off offset:64 nt
	global_load_dwordx4 v[192:195], v[232:233], off offset:512 nt
	global_load_dwordx4 v[196:199], v[232:233], off offset:576 nt
	v_lshl_add_u64 v[234:235], v[240:241], 0, v[144:145]
	global_load_dwordx4 v[200:203], v[234:235], off nt
	global_load_dwordx4 v[204:207], v[234:235], off offset:64 nt
	global_load_dwordx4 v[208:211], v[234:235], off offset:512 nt
	global_load_dwordx4 v[212:215], v[234:235], off offset:576 nt
	v_lshl_add_u64 v[236:237], v[240:241], 0, v[146:147]
	global_load_dwordx4 v[216:219], v[236:237], off nt
	global_load_dwordx4 v[220:223], v[236:237], off offset:64 nt
	global_load_dwordx4 v[224:227], v[236:237], off offset:512 nt
	global_load_dwordx4 v[228:231], v[236:237], off offset:576 nt
	s_waitcnt vmcnt(8)
	v_pk_mul_f32 v[158:159], v[158:159], 0.5 op_sel_hi:[1,0]
	v_pk_mul_f32 v[160:161], v[160:161], 0.5 op_sel_hi:[1,0]
	v_pk_mul_f32 v[162:163], v[162:163], 0.5 op_sel_hi:[1,0]
	v_pk_mul_f32 v[164:165], v[164:165], 0.5 op_sel_hi:[1,0]
	v_pk_mul_f32 v[166:167], v[166:167], 0.5 op_sel_hi:[1,0]
	v_pk_mul_f32 v[168:169], v[168:169], 0.5 op_sel_hi:[1,0]
	v_pk_mul_f32 v[170:171], v[170:171], 0.5 op_sel_hi:[1,0]
	v_pk_mul_f32 v[172:173], v[172:173], 0.5 op_sel_hi:[1,0]
	v_pk_fma_f32 v[184:185], v[126:127], v[158:159], v[184:185]
	v_pk_fma_f32 v[186:187], v[128:129], v[160:161], v[186:187]
	v_pk_fma_f32 v[188:189], v[122:123], v[162:163], v[188:189]
	v_pk_fma_f32 v[190:191], v[124:125], v[164:165], v[190:191]
	v_pk_fma_f32 v[192:193], v[118:119], v[166:167], v[192:193]
	v_pk_fma_f32 v[194:195], v[120:121], v[168:169], v[194:195]
	v_pk_fma_f32 v[196:197], v[110:111], v[170:171], v[196:197]
	v_pk_fma_f32 v[198:199], v[112:113], v[172:173], v[198:199]
	global_store_dwordx4 v[232:233], v[184:187], off
	global_store_dwordx4 v[232:233], v[188:191], off offset:64
	global_store_dwordx4 v[232:233], v[192:195], off offset:512
	global_store_dwordx4 v[232:233], v[196:199], off offset:576
	v_lshl_add_u64 v[232:233], v[240:241], 0, v[148:149]
	global_load_dwordx4 v[184:187], v[232:233], off nt
	global_load_dwordx4 v[188:191], v[232:233], off offset:64 nt
	global_load_dwordx4 v[192:195], v[232:233], off offset:512 nt
	global_load_dwordx4 v[196:199], v[232:233], off offset:576 nt
	s_waitcnt vmcnt(12)
	v_pk_fma_f32 v[200:201], v[114:115], v[158:159], v[200:201]
	v_pk_fma_f32 v[202:203], v[116:117], v[160:161], v[202:203]
	v_pk_fma_f32 v[204:205], v[106:107], v[162:163], v[204:205]
	v_pk_fma_f32 v[206:207], v[108:109], v[164:165], v[206:207]
	v_pk_fma_f32 v[208:209], v[102:103], v[166:167], v[208:209]
	v_pk_fma_f32 v[210:211], v[104:105], v[168:169], v[210:211]
	v_pk_fma_f32 v[212:213], v[94:95], v[170:171], v[212:213]
	v_pk_fma_f32 v[214:215], v[96:97], v[172:173], v[214:215]
	global_store_dwordx4 v[234:235], v[200:203], off
	global_store_dwordx4 v[234:235], v[204:207], off offset:64
	global_store_dwordx4 v[234:235], v[208:211], off offset:512
	global_store_dwordx4 v[234:235], v[212:215], off offset:576
	v_lshl_add_u64 v[234:235], v[240:241], 0, v[136:137]
	global_load_dwordx4 v[200:203], v[234:235], off nt
	global_load_dwordx4 v[204:207], v[234:235], off offset:64 nt
	global_load_dwordx4 v[208:211], v[234:235], off offset:512 nt
	global_load_dwordx4 v[212:215], v[234:235], off offset:576 nt
	s_waitcnt vmcnt(16)
	v_pk_fma_f32 v[216:217], v[98:99], v[158:159], v[216:217]
	v_pk_fma_f32 v[218:219], v[100:101], v[160:161], v[218:219]
	v_pk_fma_f32 v[220:221], v[90:91], v[162:163], v[220:221]
	v_pk_fma_f32 v[222:223], v[92:93], v[164:165], v[222:223]
	v_pk_fma_f32 v[224:225], v[86:87], v[166:167], v[224:225]
	v_pk_fma_f32 v[226:227], v[88:89], v[168:169], v[226:227]
	v_pk_fma_f32 v[228:229], v[82:83], v[170:171], v[228:229]
	v_pk_fma_f32 v[230:231], v[84:85], v[172:173], v[230:231]
	global_store_dwordx4 v[236:237], v[216:219], off
	global_store_dwordx4 v[236:237], v[220:223], off offset:64
	global_store_dwordx4 v[236:237], v[224:227], off offset:512
	global_store_dwordx4 v[236:237], v[228:231], off offset:576
	v_lshl_add_u64 v[236:237], v[240:241], 0, v[138:139]
	global_load_dwordx4 v[216:219], v[236:237], off nt
	global_load_dwordx4 v[220:223], v[236:237], off offset:64 nt
	global_load_dwordx4 v[224:227], v[236:237], off offset:512 nt
	global_load_dwordx4 v[228:231], v[236:237], off offset:576 nt
	s_waitcnt vmcnt(16)
	v_pk_fma_f32 v[184:185], v[78:79], v[158:159], v[184:185]
	v_pk_fma_f32 v[186:187], v[80:81], v[160:161], v[186:187]
	v_pk_fma_f32 v[188:189], v[74:75], v[162:163], v[188:189]
	v_pk_fma_f32 v[190:191], v[76:77], v[164:165], v[190:191]
	v_pk_fma_f32 v[192:193], v[70:71], v[166:167], v[192:193]
	v_pk_fma_f32 v[194:195], v[72:73], v[168:169], v[194:195]
	v_pk_fma_f32 v[196:197], v[66:67], v[170:171], v[196:197]
	v_pk_fma_f32 v[198:199], v[68:69], v[172:173], v[198:199]
	global_store_dwordx4 v[232:233], v[184:187], off
	global_store_dwordx4 v[232:233], v[188:191], off offset:64
	global_store_dwordx4 v[232:233], v[192:195], off offset:512
	global_store_dwordx4 v[232:233], v[196:199], off offset:576
	v_lshl_add_u64 v[232:233], v[240:241], 0, v[140:141]
	global_load_dwordx4 v[184:187], v[232:233], off nt
	global_load_dwordx4 v[188:191], v[232:233], off offset:64 nt
	global_load_dwordx4 v[192:195], v[232:233], off offset:512 nt
	global_load_dwordx4 v[196:199], v[232:233], off offset:576 nt
	s_waitcnt vmcnt(16)
	v_pk_fma_f32 v[200:201], v[62:63], v[158:159], v[200:201]
	v_pk_fma_f32 v[202:203], v[64:65], v[160:161], v[202:203]
	v_pk_fma_f32 v[204:205], v[58:59], v[162:163], v[204:205]
	v_pk_fma_f32 v[206:207], v[60:61], v[164:165], v[206:207]
	v_pk_fma_f32 v[208:209], v[54:55], v[166:167], v[208:209]
	v_pk_fma_f32 v[210:211], v[56:57], v[168:169], v[210:211]
	v_pk_fma_f32 v[212:213], v[50:51], v[170:171], v[212:213]
	v_pk_fma_f32 v[214:215], v[52:53], v[172:173], v[214:215]
	global_store_dwordx4 v[234:235], v[200:203], off
	global_store_dwordx4 v[234:235], v[204:207], off offset:64
	global_store_dwordx4 v[234:235], v[208:211], off offset:512
	global_store_dwordx4 v[234:235], v[212:215], off offset:576
	v_lshl_add_u64 v[234:235], v[240:241], 0, v[142:143]
	global_load_dwordx4 v[200:203], v[234:235], off nt
	global_load_dwordx4 v[204:207], v[234:235], off offset:64 nt
	global_load_dwordx4 v[208:211], v[234:235], off offset:512 nt
	global_load_dwordx4 v[212:215], v[234:235], off offset:576 nt
	s_waitcnt vmcnt(16)
	v_pk_fma_f32 v[216:217], v[46:47], v[158:159], v[216:217]
	v_pk_fma_f32 v[218:219], v[48:49], v[160:161], v[218:219]
	v_pk_fma_f32 v[220:221], v[42:43], v[162:163], v[220:221]
	v_pk_fma_f32 v[222:223], v[44:45], v[164:165], v[222:223]
	v_pk_fma_f32 v[224:225], v[38:39], v[166:167], v[224:225]
	v_pk_fma_f32 v[226:227], v[40:41], v[168:169], v[226:227]
	v_pk_fma_f32 v[228:229], v[30:31], v[170:171], v[228:229]
	v_pk_fma_f32 v[230:231], v[32:33], v[172:173], v[230:231]
	global_store_dwordx4 v[236:237], v[216:219], off
	global_store_dwordx4 v[236:237], v[220:223], off offset:64
	global_store_dwordx4 v[236:237], v[224:227], off offset:512
	global_store_dwordx4 v[236:237], v[228:231], off offset:576
	s_waitcnt vmcnt(12)
	v_pk_fma_f32 v[184:185], v[34:35], v[158:159], v[184:185]
	v_pk_fma_f32 v[186:187], v[36:37], v[160:161], v[186:187]
	v_pk_fma_f32 v[188:189], v[26:27], v[162:163], v[188:189]
	v_pk_fma_f32 v[190:191], v[28:29], v[164:165], v[190:191]
	v_pk_fma_f32 v[192:193], v[22:23], v[166:167], v[192:193]
	v_pk_fma_f32 v[194:195], v[24:25], v[168:169], v[194:195]
	v_pk_fma_f32 v[196:197], v[14:15], v[170:171], v[196:197]
	v_pk_fma_f32 v[198:199], v[16:17], v[172:173], v[198:199]
	global_store_dwordx4 v[232:233], v[184:187], off
	global_store_dwordx4 v[232:233], v[188:191], off offset:64
	global_store_dwordx4 v[232:233], v[192:195], off offset:512
	global_store_dwordx4 v[232:233], v[196:199], off offset:576
	s_waitcnt vmcnt(8)
	v_pk_fma_f32 v[200:201], v[18:19], v[158:159], v[200:201]
	v_pk_fma_f32 v[202:203], v[20:21], v[160:161], v[202:203]
	v_pk_fma_f32 v[204:205], v[10:11], v[162:163], v[204:205]
	v_pk_fma_f32 v[206:207], v[12:13], v[164:165], v[206:207]
	v_pk_fma_f32 v[208:209], v[6:7], v[166:167], v[208:209]
	v_pk_fma_f32 v[210:211], v[8:9], v[168:169], v[210:211]
	v_pk_fma_f32 v[212:213], v[2:3], v[170:171], v[212:213]
	v_pk_fma_f32 v[214:215], v[4:5], v[172:173], v[214:215]
	global_store_dwordx4 v[234:235], v[200:203], off
	global_store_dwordx4 v[234:235], v[204:207], off offset:64
	global_store_dwordx4 v[234:235], v[208:211], off offset:512
	global_store_dwordx4 v[234:235], v[212:215], off offset:576
	s_mov_b64 s[16:17], -1
	s_and_b64 vcc, exec, s[4:5]
	s_cbranch_vccnz .LBB0_2571
	s_andn2_b64 vcc, exec, s[8:9]
	s_cbranch_vccnz .LBB0_2570
	s_barrier
	s_branch .LBB0_2570
